# v18 + odd mixer work queue: eight per-XCD queue heads (item = 8*local + xcd) instead of one global head, to cut dequeue contention of 512 simultaneous pullers
# baseline (speedup 1.0000x reference)
.LBB0_154:
	s_and_b64 vcc, exec, s[0:1]
	s_cbranch_vccz .LBB0_188
	v_readlane_b32 s0, v232, 27
	v_readlane_b32 s1, v232, 28
	s_and_b32 s0, s0, 1
	v_writelane_b32 v232, s0, 32
	s_cmp_gt_i32 s62, 1
	s_mov_b64 s[0:1], -1
	s_cbranch_scc0 .LBB0_1084
	s_cmp_gt_i32 s62, 2
	s_cbranch_scc0 .LBB0_793
	v_readlane_b32 s0, v232, 27
	v_readlane_b32 s1, v232, 28
	s_ashr_i32 s0, s0, 1
	v_readlane_b32 s1, v232, 32
	s_cmp_lg_u32 s1, 0
	s_mov_b64 s[20:21], -1
	s_cbranch_scc0 .LBB0_190
	s_lshl_b32 s1, s0, 7
	v_readlane_b32 s20, v235, 0
	s_and_b32 s20, s20, 7
	s_lshl_b32 s20, s20, 4
	s_add_i32 s20, s20, s1
	s_addk_i32 s20, 0xf0
	s_ashr_i32 s21, s20, 31
	s_lshl_b64 s[20:21], s[20:21], 2
	v_readlane_b32 s1, v235, 46
	s_add_u32 s20, s1, s20
	v_readlane_b32 s1, v235, 47
	s_addc_u32 s21, s1, s21
	s_lshl_b32 s1, s0, 3
	s_lshl_b32 s24, s0, 12
	s_branch .LBB0_161

.LBB0_165:
	s_or_b64 exec, exec, s[28:29]
	s_waitcnt lgkmcnt(0)
	s_barrier
	ds_read_b32 v0, v162
	s_movk_i32 s25, 0x7ff
	s_mov_b64 s[28:29], -1
	s_waitcnt lgkmcnt(0)
	s_barrier
	v_readlane_b32 s2, v235, 0
	s_and_b32 s2, s2, 7
	s_nop 0
	v_lshl_add_u32 v0, v0, 3, s2
	v_cmp_lt_i32_e32 vcc, s25, v0
	v_readfirstlane_b32 s2, v0
	s_cbranch_vccnz .LBB0_160
	s_and_b32 s25, s2, 0x1ff
	s_cmpk_gt_i32 s2, 0x3ff
	s_cselect_b64 s[38:39], -1, 0
	s_and_b64 vcc, exec, s[38:39]
	s_cbranch_vccz .LBB0_168
	s_lshr_b32 s30, s25, 4
	s_lshr_b32 s31, s2, 1
	s_and_b32 s37, s2, 1
	s_lshl_b32 s36, s30, 8
	s_mov_b64 s[28:29], 0
